# sample k-loop 3-deep pipeline + first seam uses XCD barrier
# speedup vs baseline: 1.0033x; 1.0033x over previous
; template <bool GATE>
; __device__ __forceinline__ void sample_gemm_res(LAS unsigned char* lds, const bf16* Amat, const bf16* Bt, const bf16* Hin, bf16* Hout, float* rss_out, const bf16* PP, const float* rss_in, int bid, int tid) {
;     ...
;   for (int tile = bid; tile < 256; tile += (int)gridDim.x) {
;     const int m0 = TP + (tile & 7) * 64, n0 = (tile >> 3) * 64;
;     const bf16x8* ap = (const bf16x8*)(Amat + (size_t)(m0 + lr) * 2048 + wave * 256 + 8 * kg);
;     const bf16x8* bp = (const bf16x8*)(Bt + (size_t)(n0 + lr) * 2048 + wave * 256 + 8 * kg);
;     const int erow = m0 + (tid >> 3); const size_t ep = (size_t)erow * 2048 + n0 + (tid & 7) * 8;
;     const u32x4 hw = *(const u32x4*)(Hin + ep); u32x4 pw = (u32x4){0u, 0u, 0u, 0u}; float rsi = 0.f; if (GATE) { pw = *(const u32x4*)(PP + ep); rsi = rss_in[erow]; }
;     f32x4m acc[4][4];
; #pragma unroll
;     for (int mi = 0; mi < 4; ++mi)
; #pragma unroll
;         for (int ni = 0; ni < 4; ++ni) acc[mi][ni] = (f32x4m){0.f, 0.f, 0.f, 0.f};
; #pragma unroll 2
;     for (int ks = 0; ks < 8; ++ks) { bf16x8 a[4], b[4];
; #pragma unroll
;         for (int q = 0; q < 4; ++q) { a[q] = ap[(size_t)q * 16 * 256 + ks * 4]; b[q] = bp[(size_t)q * 16 * 256 + ks * 4]; }
; #pragma unroll
;         for (int mi = 0; mi < 4; ++mi)
; #pragma unroll
;             for (int ni = 0; ni < 4; ++ni) acc[mi][ni] = __builtin_amdgcn_mfma_f32_16x16x32_bf16(a[mi], b[ni], acc[mi][ni], 0, 0, 0); }
.LBB0_67:
	s_lshl_b32 s0, s6, 6
	s_and_b32 s1, s0, 0x1c0
	v_add_u32_e32 v0, s1, v88
	s_lshl_b32 s0, s6, 3
	v_add_u32_e32 v80, 0x2000, v0
	s_andn2_b32 s0, s0, 63
	v_ashrrev_i32_e32 v81, 31, v80
	v_lshlrev_b64 v[2:3], 11, v[80:81]
	s_ashr_i32 s1, s0, 31
	v_lshl_add_u64 v[82:83], v[2:3], 0, s[0:1]
	v_or_b32_e32 v82, v82, v74
	v_lshlrev_b64 v[2:3], 1, v[82:83]
	v_lshl_add_u64 v[4:5], s[46:47], 0, v[2:3]
	v_lshl_add_u64 v[2:3], s[52:53], 0, v[2:3]
	v_lshl_add_u64 v[10:11], v[80:81], 2, s[54:55]
	global_load_dwordx4 v[6:9], v[4:5], off
	s_nop 0
	global_load_dwordx4 v[2:5], v[2:3], off
	s_and_b32 s0, s3, 0xffffffc0
	global_load_dword v100, v[10:11], off
	v_or_b32_e32 v10, s0, v75
	v_ashrrev_i32_e32 v11, 31, v10
	v_lshlrev_b64 v[10:11], 12, v[10:11]
	s_and_b32 s0, s2, 0x1c0
	v_lshl_add_u64 v[84:85], v[76:77], 0, v[10:11]
	v_add_lshl_u32 v0, v95, s0, 12
	v_mov_b32_e32 v10, 0
	v_lshl_add_u64 v[86:87], v[78:79], 0, v[0:1]
	s_mov_b64 s[4:5], 0
	v_mov_b32_e32 v11, v10
	v_mov_b32_e32 v12, v10
	v_mov_b32_e32 v13, v10
	v_mov_b32_e32 v14, v10
	v_mov_b32_e32 v15, v10
	v_mov_b32_e32 v16, v10
	v_mov_b32_e32 v17, v10
	v_mov_b32_e32 v18, v10
	v_mov_b32_e32 v19, v10
	v_mov_b32_e32 v20, v10
	v_mov_b32_e32 v21, v10
	v_mov_b32_e32 v22, v10
	v_mov_b32_e32 v23, v10
	v_mov_b32_e32 v24, v10
	v_mov_b32_e32 v25, v10
	v_mov_b32_e32 v26, v10
	v_mov_b32_e32 v27, v10
	v_mov_b32_e32 v28, v10
	v_mov_b32_e32 v29, v10
	v_mov_b32_e32 v34, v10
	v_mov_b32_e32 v35, v10
	v_mov_b32_e32 v36, v10
	v_mov_b32_e32 v37, v10
	v_mov_b32_e32 v30, v10
	v_mov_b32_e32 v31, v10
	v_mov_b32_e32 v32, v10
	v_mov_b32_e32 v33, v10
	v_mov_b32_e32 v38, v10
	v_mov_b32_e32 v39, v10
	v_mov_b32_e32 v40, v10
	v_mov_b32_e32 v41, v10
	v_mov_b32_e32 v42, v10
	v_mov_b32_e32 v43, v10
	v_mov_b32_e32 v44, v10
	v_mov_b32_e32 v45, v10
	v_mov_b32_e32 v50, v10
	v_mov_b32_e32 v51, v10
	v_mov_b32_e32 v52, v10
	v_mov_b32_e32 v53, v10
	v_mov_b32_e32 v46, v10
	v_mov_b32_e32 v47, v10
	v_mov_b32_e32 v48, v10
	v_mov_b32_e32 v49, v10
	v_mov_b32_e32 v58, v10
	v_mov_b32_e32 v59, v10
	v_mov_b32_e32 v60, v10
	v_mov_b32_e32 v61, v10
	v_mov_b32_e32 v54, v10
	v_mov_b32_e32 v55, v10
	v_mov_b32_e32 v56, v10
	v_mov_b32_e32 v57, v10
	v_mov_b32_e32 v66, v10
	v_mov_b32_e32 v67, v10
	v_mov_b32_e32 v68, v10
	v_mov_b32_e32 v69, v10
	v_mov_b32_e32 v62, v10
	v_mov_b32_e32 v63, v10
	v_mov_b32_e32 v64, v10
	v_mov_b32_e32 v65, v10
	v_mov_b32_e32 v70, v10
	v_mov_b32_e32 v71, v10
	v_mov_b32_e32 v72, v10
	v_mov_b32_e32 v73, v10
	s_mov_b64 s[0:1], 0x22200000
	v_lshl_add_u64 v[134:135], v[86:87], 0, s[0:1]
	s_mov_b64 s[4:5], 0x8200000
	v_lshl_add_u64 v[136:137], v[84:85], 0, s[4:5]
	s_mov_b64 s[0:1], 0x22210000
	v_lshl_add_u64 v[138:139], v[86:87], 0, s[0:1]
	s_mov_b64 s[4:5], 0x8210000
	v_lshl_add_u64 v[140:141], v[84:85], 0, s[4:5]
	s_mov_b64 s[0:1], 0x22220000
	v_lshl_add_u64 v[142:143], v[86:87], 0, s[0:1]
	s_mov_b64 s[4:5], 0x8220000
	v_lshl_add_u64 v[144:145], v[84:85], 0, s[4:5]
	s_mov_b64 s[0:1], 0x22230000
	v_lshl_add_u64 v[146:147], v[86:87], 0, s[0:1]
	s_mov_b64 s[4:5], 0x8230000
	v_lshl_add_u64 v[148:149], v[84:85], 0, s[4:5]
	global_load_dwordx4 v[102:105], v[134:135], off
	global_load_dwordx4 v[106:109], v[136:137], off
	global_load_dwordx4 v[110:113], v[138:139], off
	global_load_dwordx4 v[114:117], v[140:141], off
	global_load_dwordx4 v[118:121], v[142:143], off
	global_load_dwordx4 v[122:125], v[144:145], off
	global_load_dwordx4 v[126:129], v[146:147], off
	global_load_dwordx4 v[130:133], v[148:149], off
	global_load_dwordx4 v[150:153], v[134:135], off offset:64
	global_load_dwordx4 v[154:157], v[136:137], off offset:64
	global_load_dwordx4 v[158:161], v[138:139], off offset:64
	global_load_dwordx4 v[162:165], v[140:141], off offset:64
	global_load_dwordx4 v[166:169], v[142:143], off offset:64
	global_load_dwordx4 v[170:173], v[144:145], off offset:64
	global_load_dwordx4 v[174:177], v[146:147], off offset:64
	global_load_dwordx4 v[178:181], v[148:149], off offset:64
	global_load_dwordx4 v[192:195], v[134:135], off offset:128
	global_load_dwordx4 v[196:199], v[136:137], off offset:128
	global_load_dwordx4 v[200:203], v[138:139], off offset:128
	global_load_dwordx4 v[204:207], v[140:141], off offset:128
	global_load_dwordx4 v[208:211], v[142:143], off offset:128
	global_load_dwordx4 v[236:239], v[144:145], off offset:128
	global_load_dwordx4 v[240:243], v[146:147], off offset:128
	global_load_dwordx4 v[244:247], v[148:149], off offset:128
	s_waitcnt vmcnt(22)
	v_mfma_f32_16x16x32_bf16 v[10:13], v[102:105], v[106:109], v[10:13]
	s_waitcnt vmcnt(20)
	v_mfma_f32_16x16x32_bf16 v[14:17], v[102:105], v[114:117], v[14:17]
	s_waitcnt vmcnt(18)
	v_mfma_f32_16x16x32_bf16 v[18:21], v[102:105], v[122:125], v[18:21]
	s_waitcnt vmcnt(16)
	v_mfma_f32_16x16x32_bf16 v[22:25], v[102:105], v[130:133], v[22:25]
	v_mfma_f32_16x16x32_bf16 v[26:29], v[110:113], v[106:109], v[26:29]
	v_mfma_f32_16x16x32_bf16 v[34:37], v[110:113], v[114:117], v[34:37]
	v_mfma_f32_16x16x32_bf16 v[30:33], v[110:113], v[122:125], v[30:33]
	v_mfma_f32_16x16x32_bf16 v[38:41], v[110:113], v[130:133], v[38:41]
	v_mfma_f32_16x16x32_bf16 v[42:45], v[118:121], v[106:109], v[42:45]
	v_mfma_f32_16x16x32_bf16 v[50:53], v[118:121], v[114:117], v[50:53]
	v_mfma_f32_16x16x32_bf16 v[46:49], v[118:121], v[122:125], v[46:49]
	v_mfma_f32_16x16x32_bf16 v[58:61], v[118:121], v[130:133], v[58:61]
	v_mfma_f32_16x16x32_bf16 v[54:57], v[126:129], v[106:109], v[54:57]
	v_mfma_f32_16x16x32_bf16 v[66:69], v[126:129], v[114:117], v[66:69]
	v_mfma_f32_16x16x32_bf16 v[62:65], v[126:129], v[122:125], v[62:65]
	v_mfma_f32_16x16x32_bf16 v[70:73], v[126:129], v[130:133], v[70:73]
	global_load_dwordx4 v[102:105], v[134:135], off offset:192
	global_load_dwordx4 v[106:109], v[136:137], off offset:192
	global_load_dwordx4 v[110:113], v[138:139], off offset:192
	global_load_dwordx4 v[114:117], v[140:141], off offset:192
	global_load_dwordx4 v[118:121], v[142:143], off offset:192
	global_load_dwordx4 v[122:125], v[144:145], off offset:192
	global_load_dwordx4 v[126:129], v[146:147], off offset:192
	global_load_dwordx4 v[130:133], v[148:149], off offset:192
	s_waitcnt vmcnt(22)
; template <bool GATE>
; __device__ __forceinline__ void sample_gemm_res(LAS unsigned char* lds, const bf16* Amat, const bf16* Bt, const bf16* Hin, bf16* Hout, float* rss_out, const bf16* PP, const float* rss_in, int bid, int tid) {
;     ...
;     for (int ks = 0; ks < 8; ++ks) { bf16x8 a[4], b[4];
; #pragma unroll
;         for (int q = 0; q < 4; ++q) { a[q] = ap[(size_t)q * 16 * 256 + ks * 4]; b[q] = bp[(size_t)q * 16 * 256 + ks * 4]; }
; #pragma unroll
;         for (int mi = 0; mi < 4; ++mi)
; #pragma unroll
;             for (int ni = 0; ni < 4; ++ni) acc[mi][ni] = __builtin_amdgcn_mfma_f32_16x16x32_bf16(a[mi], b[ni], acc[mi][ni], 0, 0, 0); }
	v_mfma_f32_16x16x32_bf16 v[10:13], v[150:153], v[154:157], v[10:13]
	s_waitcnt vmcnt(20)
	v_mfma_f32_16x16x32_bf16 v[14:17], v[150:153], v[162:165], v[14:17]
	s_waitcnt vmcnt(18)
	v_mfma_f32_16x16x32_bf16 v[18:21], v[150:153], v[170:173], v[18:21]
	s_waitcnt vmcnt(16)
	v_mfma_f32_16x16x32_bf16 v[22:25], v[150:153], v[178:181], v[22:25]
	v_mfma_f32_16x16x32_bf16 v[26:29], v[158:161], v[154:157], v[26:29]
	v_mfma_f32_16x16x32_bf16 v[34:37], v[158:161], v[162:165], v[34:37]
	v_mfma_f32_16x16x32_bf16 v[30:33], v[158:161], v[170:173], v[30:33]
	v_mfma_f32_16x16x32_bf16 v[38:41], v[158:161], v[178:181], v[38:41]
	v_mfma_f32_16x16x32_bf16 v[42:45], v[166:169], v[154:157], v[42:45]
	v_mfma_f32_16x16x32_bf16 v[50:53], v[166:169], v[162:165], v[50:53]
	v_mfma_f32_16x16x32_bf16 v[46:49], v[166:169], v[170:173], v[46:49]
	v_mfma_f32_16x16x32_bf16 v[58:61], v[166:169], v[178:181], v[58:61]
	v_mfma_f32_16x16x32_bf16 v[54:57], v[174:177], v[154:157], v[54:57]
	v_mfma_f32_16x16x32_bf16 v[66:69], v[174:177], v[162:165], v[66:69]
	v_mfma_f32_16x16x32_bf16 v[62:65], v[174:177], v[170:173], v[62:65]
	v_mfma_f32_16x16x32_bf16 v[70:73], v[174:177], v[178:181], v[70:73]
	global_load_dwordx4 v[150:153], v[134:135], off offset:256
	global_load_dwordx4 v[154:157], v[136:137], off offset:256
	global_load_dwordx4 v[158:161], v[138:139], off offset:256
	global_load_dwordx4 v[162:165], v[140:141], off offset:256
	global_load_dwordx4 v[166:169], v[142:143], off offset:256
	global_load_dwordx4 v[170:173], v[144:145], off offset:256
	global_load_dwordx4 v[174:177], v[146:147], off offset:256
	global_load_dwordx4 v[178:181], v[148:149], off offset:256
	s_waitcnt vmcnt(22)
	v_mfma_f32_16x16x32_bf16 v[10:13], v[192:195], v[196:199], v[10:13]
	s_waitcnt vmcnt(20)
	v_mfma_f32_16x16x32_bf16 v[14:17], v[192:195], v[204:207], v[14:17]
	s_waitcnt vmcnt(18)
	v_mfma_f32_16x16x32_bf16 v[18:21], v[192:195], v[236:239], v[18:21]
	s_waitcnt vmcnt(16)
	v_mfma_f32_16x16x32_bf16 v[22:25], v[192:195], v[244:247], v[22:25]
	v_mfma_f32_16x16x32_bf16 v[26:29], v[200:203], v[196:199], v[26:29]
	v_mfma_f32_16x16x32_bf16 v[34:37], v[200:203], v[204:207], v[34:37]
	v_mfma_f32_16x16x32_bf16 v[30:33], v[200:203], v[236:239], v[30:33]
	v_mfma_f32_16x16x32_bf16 v[38:41], v[200:203], v[244:247], v[38:41]
	v_mfma_f32_16x16x32_bf16 v[42:45], v[208:211], v[196:199], v[42:45]
	v_mfma_f32_16x16x32_bf16 v[50:53], v[208:211], v[204:207], v[50:53]
	v_mfma_f32_16x16x32_bf16 v[46:49], v[208:211], v[236:239], v[46:49]
	v_mfma_f32_16x16x32_bf16 v[58:61], v[208:211], v[244:247], v[58:61]
	v_mfma_f32_16x16x32_bf16 v[54:57], v[240:243], v[196:199], v[54:57]
	v_mfma_f32_16x16x32_bf16 v[66:69], v[240:243], v[204:207], v[66:69]
	v_mfma_f32_16x16x32_bf16 v[62:65], v[240:243], v[236:239], v[62:65]
	v_mfma_f32_16x16x32_bf16 v[70:73], v[240:243], v[244:247], v[70:73]
	global_load_dwordx4 v[192:195], v[134:135], off offset:320
	global_load_dwordx4 v[196:199], v[136:137], off offset:320
	global_load_dwordx4 v[200:203], v[138:139], off offset:320
	global_load_dwordx4 v[204:207], v[140:141], off offset:320
	global_load_dwordx4 v[208:211], v[142:143], off offset:320
	global_load_dwordx4 v[236:239], v[144:145], off offset:320
	global_load_dwordx4 v[240:243], v[146:147], off offset:320
	global_load_dwordx4 v[244:247], v[148:149], off offset:320
	s_waitcnt vmcnt(22)
	v_mfma_f32_16x16x32_bf16 v[10:13], v[102:105], v[106:109], v[10:13]
	s_waitcnt vmcnt(20)
	v_mfma_f32_16x16x32_bf16 v[14:17], v[102:105], v[114:117], v[14:17]
	s_waitcnt vmcnt(18)
	v_mfma_f32_16x16x32_bf16 v[18:21], v[102:105], v[122:125], v[18:21]
	s_waitcnt vmcnt(16)
	v_mfma_f32_16x16x32_bf16 v[22:25], v[102:105], v[130:133], v[22:25]
	v_mfma_f32_16x16x32_bf16 v[26:29], v[110:113], v[106:109], v[26:29]
	v_mfma_f32_16x16x32_bf16 v[34:37], v[110:113], v[114:117], v[34:37]
	v_mfma_f32_16x16x32_bf16 v[30:33], v[110:113], v[122:125], v[30:33]
	v_mfma_f32_16x16x32_bf16 v[38:41], v[110:113], v[130:133], v[38:41]
	v_mfma_f32_16x16x32_bf16 v[42:45], v[118:121], v[106:109], v[42:45]
	v_mfma_f32_16x16x32_bf16 v[50:53], v[118:121], v[114:117], v[50:53]
	v_mfma_f32_16x16x32_bf16 v[46:49], v[118:121], v[122:125], v[46:49]
	v_mfma_f32_16x16x32_bf16 v[58:61], v[118:121], v[130:133], v[58:61]
	v_mfma_f32_16x16x32_bf16 v[54:57], v[126:129], v[106:109], v[54:57]
	v_mfma_f32_16x16x32_bf16 v[66:69], v[126:129], v[114:117], v[66:69]
	v_mfma_f32_16x16x32_bf16 v[62:65], v[126:129], v[122:125], v[62:65]
	v_mfma_f32_16x16x32_bf16 v[70:73], v[126:129], v[130:133], v[70:73]
	global_load_dwordx4 v[102:105], v[134:135], off offset:384
	global_load_dwordx4 v[106:109], v[136:137], off offset:384
	global_load_dwordx4 v[110:113], v[138:139], off offset:384
	global_load_dwordx4 v[114:117], v[140:141], off offset:384
	global_load_dwordx4 v[118:121], v[142:143], off offset:384
	global_load_dwordx4 v[122:125], v[144:145], off offset:384
	global_load_dwordx4 v[126:129], v[146:147], off offset:384
	global_load_dwordx4 v[130:133], v[148:149], off offset:384
	s_waitcnt vmcnt(22)
	v_mfma_f32_16x16x32_bf16 v[10:13], v[150:153], v[154:157], v[10:13]
	s_waitcnt vmcnt(20)
	v_mfma_f32_16x16x32_bf16 v[14:17], v[150:153], v[162:165], v[14:17]
	s_waitcnt vmcnt(18)
	v_mfma_f32_16x16x32_bf16 v[18:21], v[150:153], v[170:173], v[18:21]
	s_waitcnt vmcnt(16)
; #define LAS __attribute__((address_space(3)))
; template <bool GATE>
; __device__ __forceinline__ void sample_gemm_res(LAS unsigned char* lds, const bf16* Amat, const bf16* Bt, const bf16* Hin, bf16* Hout, float* rss_out, const bf16* PP, const float* rss_in, int bid, int tid) {
;     ...
;     for (int ks = 0; ks < 8; ++ks) { bf16x8 a[4], b[4];
; #pragma unroll
;         for (int q = 0; q < 4; ++q) { a[q] = ap[(size_t)q * 16 * 256 + ks * 4]; b[q] = bp[(size_t)q * 16 * 256 + ks * 4]; }
; #pragma unroll
;         for (int mi = 0; mi < 4; ++mi)
; #pragma unroll
;             for (int ni = 0; ni < 4; ++ni) acc[mi][ni] = __builtin_amdgcn_mfma_f32_16x16x32_bf16(a[mi], b[ni], acc[mi][ni], 0, 0, 0); }
;     LAS float* red = (LAS float*)lds;
;     __syncthreads();
	v_mfma_f32_16x16x32_bf16 v[22:25], v[150:153], v[178:181], v[22:25]
	v_mfma_f32_16x16x32_bf16 v[26:29], v[158:161], v[154:157], v[26:29]
	v_mfma_f32_16x16x32_bf16 v[34:37], v[158:161], v[162:165], v[34:37]
	v_mfma_f32_16x16x32_bf16 v[30:33], v[158:161], v[170:173], v[30:33]
	v_mfma_f32_16x16x32_bf16 v[38:41], v[158:161], v[178:181], v[38:41]
	v_mfma_f32_16x16x32_bf16 v[42:45], v[166:169], v[154:157], v[42:45]
	v_mfma_f32_16x16x32_bf16 v[50:53], v[166:169], v[162:165], v[50:53]
	v_mfma_f32_16x16x32_bf16 v[46:49], v[166:169], v[170:173], v[46:49]
	v_mfma_f32_16x16x32_bf16 v[58:61], v[166:169], v[178:181], v[58:61]
	v_mfma_f32_16x16x32_bf16 v[54:57], v[174:177], v[154:157], v[54:57]
	v_mfma_f32_16x16x32_bf16 v[66:69], v[174:177], v[162:165], v[66:69]
	v_mfma_f32_16x16x32_bf16 v[62:65], v[174:177], v[170:173], v[62:65]
	v_mfma_f32_16x16x32_bf16 v[70:73], v[174:177], v[178:181], v[70:73]
	global_load_dwordx4 v[150:153], v[134:135], off offset:448
	global_load_dwordx4 v[154:157], v[136:137], off offset:448
	global_load_dwordx4 v[158:161], v[138:139], off offset:448
	global_load_dwordx4 v[162:165], v[140:141], off offset:448
	global_load_dwordx4 v[166:169], v[142:143], off offset:448
	global_load_dwordx4 v[170:173], v[144:145], off offset:448
	global_load_dwordx4 v[174:177], v[146:147], off offset:448
	global_load_dwordx4 v[178:181], v[148:149], off offset:448
	s_waitcnt vmcnt(22)
	v_mfma_f32_16x16x32_bf16 v[10:13], v[192:195], v[196:199], v[10:13]
	s_waitcnt vmcnt(20)
	v_mfma_f32_16x16x32_bf16 v[14:17], v[192:195], v[204:207], v[14:17]
	s_waitcnt vmcnt(18)
	v_mfma_f32_16x16x32_bf16 v[18:21], v[192:195], v[236:239], v[18:21]
	s_waitcnt vmcnt(16)
	v_mfma_f32_16x16x32_bf16 v[22:25], v[192:195], v[244:247], v[22:25]
	v_mfma_f32_16x16x32_bf16 v[26:29], v[200:203], v[196:199], v[26:29]
	v_mfma_f32_16x16x32_bf16 v[34:37], v[200:203], v[204:207], v[34:37]
	v_mfma_f32_16x16x32_bf16 v[30:33], v[200:203], v[236:239], v[30:33]
	v_mfma_f32_16x16x32_bf16 v[38:41], v[200:203], v[244:247], v[38:41]
	v_mfma_f32_16x16x32_bf16 v[42:45], v[208:211], v[196:199], v[42:45]
	v_mfma_f32_16x16x32_bf16 v[50:53], v[208:211], v[204:207], v[50:53]
	v_mfma_f32_16x16x32_bf16 v[46:49], v[208:211], v[236:239], v[46:49]
	v_mfma_f32_16x16x32_bf16 v[58:61], v[208:211], v[244:247], v[58:61]
	v_mfma_f32_16x16x32_bf16 v[54:57], v[240:243], v[196:199], v[54:57]
	v_mfma_f32_16x16x32_bf16 v[66:69], v[240:243], v[204:207], v[66:69]
	v_mfma_f32_16x16x32_bf16 v[62:65], v[240:243], v[236:239], v[62:65]
	v_mfma_f32_16x16x32_bf16 v[70:73], v[240:243], v[244:247], v[70:73]
	s_waitcnt vmcnt(14)
	v_mfma_f32_16x16x32_bf16 v[10:13], v[102:105], v[106:109], v[10:13]
	s_waitcnt vmcnt(12)
	v_mfma_f32_16x16x32_bf16 v[14:17], v[102:105], v[114:117], v[14:17]
	s_waitcnt vmcnt(10)
	v_mfma_f32_16x16x32_bf16 v[18:21], v[102:105], v[122:125], v[18:21]
	s_waitcnt vmcnt(8)
	v_mfma_f32_16x16x32_bf16 v[22:25], v[102:105], v[130:133], v[22:25]
	v_mfma_f32_16x16x32_bf16 v[26:29], v[110:113], v[106:109], v[26:29]
	v_mfma_f32_16x16x32_bf16 v[34:37], v[110:113], v[114:117], v[34:37]
	v_mfma_f32_16x16x32_bf16 v[30:33], v[110:113], v[122:125], v[30:33]
	v_mfma_f32_16x16x32_bf16 v[38:41], v[110:113], v[130:133], v[38:41]
	v_mfma_f32_16x16x32_bf16 v[42:45], v[118:121], v[106:109], v[42:45]
	v_mfma_f32_16x16x32_bf16 v[50:53], v[118:121], v[114:117], v[50:53]
	v_mfma_f32_16x16x32_bf16 v[46:49], v[118:121], v[122:125], v[46:49]
	v_mfma_f32_16x16x32_bf16 v[58:61], v[118:121], v[130:133], v[58:61]
	v_mfma_f32_16x16x32_bf16 v[54:57], v[126:129], v[106:109], v[54:57]
	v_mfma_f32_16x16x32_bf16 v[66:69], v[126:129], v[114:117], v[66:69]
	v_mfma_f32_16x16x32_bf16 v[62:65], v[126:129], v[122:125], v[62:65]
	v_mfma_f32_16x16x32_bf16 v[70:73], v[126:129], v[130:133], v[70:73]
	s_waitcnt vmcnt(6)
	v_mfma_f32_16x16x32_bf16 v[10:13], v[150:153], v[154:157], v[10:13]
	s_waitcnt vmcnt(4)
	v_mfma_f32_16x16x32_bf16 v[14:17], v[150:153], v[162:165], v[14:17]
	s_waitcnt vmcnt(2)
	v_mfma_f32_16x16x32_bf16 v[18:21], v[150:153], v[170:173], v[18:21]
	s_waitcnt vmcnt(0)
	v_mfma_f32_16x16x32_bf16 v[22:25], v[150:153], v[178:181], v[22:25]
	v_mfma_f32_16x16x32_bf16 v[26:29], v[158:161], v[154:157], v[26:29]
	v_mfma_f32_16x16x32_bf16 v[34:37], v[158:161], v[162:165], v[34:37]
	v_mfma_f32_16x16x32_bf16 v[30:33], v[158:161], v[170:173], v[30:33]
	v_mfma_f32_16x16x32_bf16 v[38:41], v[158:161], v[178:181], v[38:41]
	v_mfma_f32_16x16x32_bf16 v[42:45], v[166:169], v[154:157], v[42:45]
	v_mfma_f32_16x16x32_bf16 v[50:53], v[166:169], v[162:165], v[50:53]
	v_mfma_f32_16x16x32_bf16 v[46:49], v[166:169], v[170:173], v[46:49]
	v_mfma_f32_16x16x32_bf16 v[58:61], v[166:169], v[178:181], v[58:61]
	v_mfma_f32_16x16x32_bf16 v[54:57], v[174:177], v[154:157], v[54:57]
	v_mfma_f32_16x16x32_bf16 v[66:69], v[174:177], v[162:165], v[66:69]
	v_mfma_f32_16x16x32_bf16 v[62:65], v[174:177], v[170:173], v[62:65]
	v_mfma_f32_16x16x32_bf16 v[70:73], v[174:177], v[178:181], v[70:73]
	v_add_u32_e32 v0, 0x1000, v93
	s_barrier
; template <bool GATE>
; __device__ __forceinline__ void sample_gemm_res(LAS unsigned char* lds, const bf16* Amat, const bf16* Bt, const bf16* Hin, bf16* Hout, float* rss_out, const bf16* PP, const float* rss_in, int bid, int tid) {
;     ...
; #pragma unroll
;     for (int mi = 0; mi < 4; ++mi)
; #pragma unroll
;         for (int ni = 0; ni < 4; ++ni)
; #pragma unroll
;             for (int i = 0; i < 4; ++i) red[(wave * 64 + 16 * mi + kg * 4 + i) * 65 + 16 * ni + lr] = acc[mi][ni][i];
;     __syncthreads();
	ds_write2_b32 v93, v10, v14 offset1:16
	ds_write2_b32 v93, v11, v15 offset0:65 offset1:81
	ds_write2_b32 v93, v12, v16 offset0:130 offset1:146
	ds_write2_b32 v93, v13, v17 offset0:195 offset1:211
	ds_write2_b32 v93, v18, v22 offset0:32 offset1:48
	ds_write2_b32 v93, v19, v23 offset0:97 offset1:113
	ds_write2_b32 v93, v20, v24 offset0:162 offset1:178
	ds_write2_b32 v93, v21, v25 offset0:227 offset1:243
	ds_write2_b32 v0, v26, v34 offset0:16 offset1:32
	ds_write2_b32 v0, v27, v35 offset0:81 offset1:97
	ds_write2_b32 v0, v28, v36 offset0:146 offset1:162
	ds_write2_b32 v0, v29, v37 offset0:211 offset1:227
	ds_write2_b32 v0, v30, v38 offset0:48 offset1:64
	ds_write2_b32 v0, v31, v39 offset0:113 offset1:129
	ds_write2_b32 v0, v32, v40 offset0:178 offset1:194
	v_add_u32_e32 v0, 0x1200, v93
	ds_write2_b32 v0, v33, v41 offset0:115 offset1:131
	v_add_u32_e32 v0, 0x2000, v93
	ds_write2_b32 v0, v42, v50 offset0:32 offset1:48
	ds_write2_b32 v0, v43, v51 offset0:97 offset1:113
	ds_write2_b32 v0, v44, v52 offset0:162 offset1:178
	ds_write2_b32 v0, v45, v53 offset0:227 offset1:243
	ds_write2_b32 v0, v46, v58 offset0:64 offset1:80
	ds_write2_b32 v0, v47, v59 offset0:129 offset1:145
	ds_write2_b32 v0, v48, v60 offset0:194 offset1:210
	v_add_u32_e32 v0, 0x2400, v93
	ds_write2_b32 v0, v49, v61 offset0:3 offset1:19
	v_add_u32_e32 v0, 0x3000, v93
	v_add_u32_e32 v10, 0x3200, v93
	ds_write2_b32 v0, v54, v66 offset0:48 offset1:64
	ds_write2_b32 v0, v55, v67 offset0:113 offset1:129
	ds_write2_b32 v0, v56, v68 offset0:178 offset1:194
	ds_write2_b32 v10, v57, v69 offset0:115 offset1:131
	ds_write2_b32 v0, v62, v70 offset0:80 offset1:96
	ds_write2_b32 v0, v63, v71 offset0:145 offset1:161
	ds_write2_b32 v0, v64, v72 offset0:210 offset1:226
	v_add_u32_e32 v0, 0x3400, v93
	ds_write2_b32 v0, v65, v73 offset0:19 offset1:35
	v_add_u32_e32 v0, v89, v94
	s_waitcnt lgkmcnt(0)
	s_barrier
; __device__ __forceinline__ unsigned cvtpk(float lo, float hi) { f32x2_t v = {lo, hi}; bf16x2_t b = __builtin_convertvector(v, bf16x2_t); return __builtin_bit_cast(unsigned, b); }
; template <bool GATE>
; __device__ __forceinline__ void sample_gemm_res(LAS unsigned char* lds, const bf16* Amat, const bf16* Bt, const bf16* Hin, bf16* Hout, float* rss_out, const bf16* PP, const float* rss_in, int bid, int tid) {
;     ...
;     { const int row = tid >> 3, c8 = (tid & 7) * 8, grow = m0 + row; float v[8];
; #pragma unroll
;       for (int e = 0; e < 8; ++e) { float sacc = 0.f;
; #pragma unroll
;           for (int w = 0; w < 8; ++w) sacc += red[(w * 64 + row) * 65 + c8 + e];
;           v[e] = sacc; }
;       float sc = 1.f; if (GATE) sc = rsqrtf(rsi * (1.f / 2048.f) + 1e-6f);
;       const size_t p = (size_t)grow * 2048 + n0 + c8;
;       const unsigned hws[4] = {hw.x, hw.y, hw.z, hw.w}, pws[4] = {pw.x, pw.y, pw.z, pw.w}; unsigned ow[4]; float sq = 0.f;
; #pragma unroll
;       for (int e2 = 0; e2 < 4; ++e2) { float h0 = __uint_as_float(hws[e2] << 16), h1 = __uint_as_float(hws[e2] & 0xffff0000u);
;           if (GATE) { h0 += __builtin_amdgcn_rcpf(1.f + __expf(-sc * v[2 * e2])) * __uint_as_float(pws[e2] << 16); h1 += __builtin_amdgcn_rcpf(1.f + __expf(-sc * v[2 * e2 + 1])) * __uint_as_float(pws[e2] & 0xffff0000u); }
;           else { h0 += v[2 * e2]; h1 += v[2 * e2 + 1]; }
;           sq += h0 * h0 + h1 * h1; ow[e2] = cvtpk(h0, h1); }
;       *(u32x4*)(Hout + p) = (u32x4){ow[0], ow[1], ow[2], ow[3]};
;       sq += __shfl_xor(sq, 1); sq += __shfl_xor(sq, 2); sq += __shfl_xor(sq, 4);
;       if ((tid & 7) == 0) atomicAdd(rss_out + grow, sq); }
;     __syncthreads();
	ds_read2_b32 v[10:11], v0 offset1:1
	v_add_u32_e32 v12, 0x4100, v0
	v_add_u32_e32 v14, 0x8200, v0
	v_add_u32_e32 v16, 0xc300, v0
	ds_read2_b32 v[12:13], v12 offset1:1
	ds_read2_b32 v[14:15], v14 offset1:1
	ds_read2_b32 v[16:17], v16 offset1:1
	ds_read2_b32 v[18:19], v0 offset0:2 offset1:3
	ds_read2_b32 v[20:21], v0 offset0:4 offset1:5
	ds_read2_b32 v[22:23], v0 offset0:6 offset1:7
	ds_read2_b32 v[24:25], v96 offset1:1
	ds_read2_b32 v[26:27], v97 offset1:1
	s_waitcnt lgkmcnt(8)
	v_add_f32_e32 v10, 0, v10
	s_waitcnt lgkmcnt(7)
	v_add_f32_e32 v10, v10, v12
	s_waitcnt lgkmcnt(6)
	v_add_f32_e32 v10, v10, v14
	s_waitcnt lgkmcnt(5)
	v_add_f32_e32 v10, v10, v16
	s_waitcnt lgkmcnt(1)
	v_add_f32_e32 v10, v10, v24
	ds_read2_b32 v[28:29], v96 offset0:2 offset1:3
	ds_read2_b32 v[30:31], v96 offset0:4 offset1:5
	ds_read2_b32 v[32:33], v96 offset0:6 offset1:7
	s_waitcnt lgkmcnt(3)
	v_add_f32_e32 v10, v10, v26
	ds_read2_b32 v[34:35], v98 offset1:1
	ds_read2_b32 v[36:37], v99 offset1:1
	ds_read2_b32 v[38:39], v97 offset0:2 offset1:3
	ds_read2_b32 v[40:41], v97 offset0:4 offset1:5
	ds_read2_b32 v[42:43], v97 offset0:6 offset1:7
	s_waitcnt lgkmcnt(4)
	v_add_f32_e32 v10, v10, v34
	s_waitcnt lgkmcnt(3)
	v_add_f32_e32 v50, v10, v36
	v_add_f32_e32 v10, 0, v11
	v_add_f32_e32 v10, v10, v13
	v_add_f32_e32 v10, v10, v15
	v_add_f32_e32 v10, v10, v17
	v_add_f32_e32 v10, v10, v25
	v_add_f32_e32 v10, v10, v27
	v_add_f32_e32 v10, v10, v35
	v_add_f32_e32 v51, v10, v37
	v_add_u32_e32 v10, 0x4108, v0
	ds_read2_b32 v[44:45], v98 offset0:2 offset1:3
	ds_read2_b32 v[46:47], v98 offset0:4 offset1:5
	ds_read2_b32 v[48:49], v98 offset0:6 offset1:7
	ds_read2_b32 v[10:11], v10 offset1:1
	v_add_f32_e32 v18, 0, v18
	v_add_u32_e32 v26, 0xc308, v0
	ds_read2_b32 v[12:13], v99 offset0:2 offset1:3
	ds_read2_b32 v[14:15], v99 offset0:4 offset1:5
	ds_read2_b32 v[16:17], v99 offset0:6 offset1:7
	v_add_u32_e32 v36, 0x8210, v0
	s_waitcnt lgkmcnt(3)
	v_add_f32_e32 v10, v18, v10
	v_add_u32_e32 v18, 0x8208, v0
	ds_read2_b32 v[24:25], v18 offset1:1
	ds_read2_b32 v[26:27], v26 offset1:1
	v_add_u32_e32 v18, 0x4110, v0
	ds_read2_b32 v[34:35], v18 offset1:1
	ds_read2_b32 v[36:37], v36 offset1:1
	v_add_u32_e32 v18, 0x8218, v0
	s_waitcnt lgkmcnt(3)
	v_add_f32_e32 v10, v10, v24
	s_waitcnt lgkmcnt(2)
	v_add_f32_e32 v10, v10, v26
	v_add_f32_e32 v10, v10, v28
	v_add_f32_e32 v10, v10, v38
	v_add_f32_e32 v10, v10, v44
	v_add_f32_e32 v26, v10, v12
	v_add_f32_e32 v10, 0, v19
	v_add_f32_e32 v10, v10, v11
	v_add_f32_e32 v10, v10, v25
	v_add_f32_e32 v10, v10, v27
	v_add_f32_e32 v10, v10, v29
	v_add_f32_e32 v10, v10, v39
	v_add_f32_e32 v10, v10, v45
	v_add_f32_e32 v27, v10, v13
	v_add_f32_e32 v10, 0, v20
	s_waitcnt lgkmcnt(1)
	v_add_f32_e32 v10, v10, v34
	s_waitcnt lgkmcnt(0)
	v_add_f32_e32 v20, v10, v36
	v_add_u32_e32 v10, 0xc310, v0
	ds_read2_b32 v[10:11], v10 offset1:1
	v_add_u32_e32 v12, 0x4118, v0
	v_add_u32_e32 v0, 0xc318, v0
	ds_read2_b32 v[12:13], v12 offset1:1
	ds_read2_b32 v[18:19], v18 offset1:1
	ds_read2_b32 v[24:25], v0 offset1:1
	s_waitcnt lgkmcnt(3)
	v_add_f32_e32 v0, v20, v10
	v_add_f32_e32 v10, 0, v21
	v_add_f32_e32 v10, v10, v35
	v_add_f32_e32 v10, v10, v37
	v_add_f32_e32 v10, v10, v11
	v_add_f32_e32 v10, v10, v31
	v_add_f32_e32 v10, v10, v41
	v_add_f32_e32 v10, v10, v47
	v_add_f32_e32 v20, v10, v15
	v_add_f32_e32 v10, 0, v22
	v_fmamk_f32 v11, v100, 0x3a000000, v214
	s_waitcnt lgkmcnt(2)
	v_add_f32_e32 v10, v10, v12
	v_mul_f32_e32 v12, 0x4b800000, v11
	v_cmp_gt_f32_e64 s[40:41], s65, v11
	s_waitcnt lgkmcnt(1)
	v_add_f32_e32 v10, v10, v18
	s_waitcnt lgkmcnt(0)
	v_add_f32_e32 v10, v10, v24
	v_cndmask_b32_e64 v11, v11, v12, s[40:41]
	v_rsq_f32_e32 v11, v11
	v_add_f32_e32 v10, v10, v32
	v_add_f32_e32 v10, v10, v42
	v_add_f32_e32 v10, v10, v48
	v_mul_f32_e32 v12, 0x45800000, v11
	v_add_f32_e32 v21, v10, v16
	v_add_f32_e32 v10, 0, v23
	v_cndmask_b32_e64 v22, v11, v12, s[40:41]
	v_add_f32_e32 v10, v10, v13
	v_mul_f32_e64 v11, v50, -v22
	v_mul_f32_e64 v12, v51, -v22
	v_add_f32_e32 v10, v10, v19
	v_mul_f32_e32 v11, 0x3fb8aa3b, v11
	v_mul_f32_e32 v12, 0x3fb8aa3b, v12
	v_add_f32_e32 v0, v0, v30
	v_add_f32_e32 v10, v10, v25
	v_exp_f32_e32 v11, v11
	v_exp_f32_e32 v12, v12
	v_add_f32_e32 v0, v0, v40
	v_add_f32_e32 v10, v10, v33
	v_add_f32_e32 v0, v0, v46
	v_add_f32_e32 v10, v10, v43
	v_add_f32_e32 v0, v0, v14
	v_add_f32_e32 v10, v10, v49
	v_lshlrev_b32_e32 v14, 16, v2
	v_and_b32_e32 v15, 0xffff0000, v2
	v_mul_f32_e64 v2, v26, -v22
	v_add_f32_e32 v23, v10, v17
	v_add_f32_e32 v10, 1.0, v11
	v_add_f32_e32 v11, 1.0, v12
	v_lshlrev_b32_e32 v12, 16, v6
	v_and_b32_e32 v13, 0xffff0000, v6
	v_mul_f32_e32 v2, 0x3fb8aa3b, v2
	v_mul_f32_e64 v6, v27, -v22
	v_exp_f32_e32 v2, v2
	v_mul_f32_e32 v6, 0x3fb8aa3b, v6
	v_rcp_f32_e32 v10, v10
	v_rcp_f32_e32 v11, v11
	v_exp_f32_e32 v6, v6
	v_add_f32_e32 v2, 1.0, v2
	v_mul_f32_e64 v0, v0, -v22
	v_pk_fma_f32 v[10:11], v[10:11], v[14:15], v[12:13]
	v_rcp_f32_e32 v14, v2
	v_add_f32_e32 v2, 1.0, v6
	v_rcp_f32_e32 v15, v2
	v_lshlrev_b32_e32 v6, 16, v7
	v_and_b32_e32 v7, 0xffff0000, v7
	v_lshlrev_b32_e32 v2, 16, v3
	v_and_b32_e32 v3, 0xffff0000, v3
	v_pk_fma_f32 v[2:3], v[14:15], v[2:3], v[6:7]
	v_mul_f32_e32 v0, 0x3fb8aa3b, v0
	v_mul_f32_e64 v6, v20, -v22
	v_exp_f32_e32 v0, v0
	v_mul_f32_e32 v6, 0x3fb8aa3b, v6
	v_exp_f32_e32 v15, v6
	v_lshlrev_b32_e32 v18, 16, v4
	v_add_f32_e32 v0, 1.0, v0
	v_rcp_f32_e32 v14, v0
	v_add_f32_e32 v0, 1.0, v15
	v_rcp_f32_e32 v15, v0
	v_mul_f32_e64 v0, v21, -v22
	v_and_b32_e32 v19, 0xffff0000, v4
	v_mul_f32_e32 v0, 0x3fb8aa3b, v0
	v_mul_f32_e64 v4, v23, -v22
	v_exp_f32_e32 v0, v0
	v_mul_f32_e32 v4, 0x3fb8aa3b, v4
	v_exp_f32_e32 v4, v4
	v_lshlrev_b32_e32 v16, 16, v8
	v_and_b32_e32 v17, 0xffff0000, v8
	v_add_f32_e32 v0, 1.0, v0
	v_pk_fma_f32 v[14:15], v[14:15], v[18:19], v[16:17]
	v_rcp_f32_e32 v18, v0
	v_add_f32_e32 v0, 1.0, v4
	v_rcp_f32_e32 v19, v0
	v_pk_mul_f32 v[12:13], v[10:11], v[10:11]
	v_pk_mul_f32 v[6:7], v[2:3], v[2:3]
	v_lshlrev_b32_e32 v8, 16, v9
	v_and_b32_e32 v9, 0xffff0000, v9
	v_lshlrev_b32_e32 v4, 16, v5
	v_and_b32_e32 v5, 0xffff0000, v5
	v_pk_mul_f32 v[16:17], v[14:15], v[14:15]
	v_pk_fma_f32 v[8:9], v[18:19], v[4:5], v[8:9]
	v_add_f32_e32 v0, v6, v7
	v_add_f32_e32 v6, v12, v13
	v_pk_mul_f32 v[4:5], v[8:9], v[8:9]
	v_add_f32_e32 v0, v6, v0
	v_add_f32_e32 v6, v16, v17
	v_add_f32_e32 v0, v0, v6
	v_add_f32_e32 v4, v4, v5
	v_add_f32_e32 v0, v0, v4
	ds_bpermute_b32 v4, v90, v0
	v_cvt_pk_bf16_f32 v5, v2, v3
	v_cvt_pk_bf16_f32 v7, v8, v9
	v_lshl_add_u64 v[8:9], v[82:83], 1, s[48:49]
	s_waitcnt lgkmcnt(0)
	v_add_f32_e32 v0, v0, v4
	ds_bpermute_b32 v6, v91, v0
	v_cvt_pk_bf16_f32 v4, v10, v11
	s_waitcnt lgkmcnt(0)
	v_add_f32_e32 v0, v0, v6
	ds_bpermute_b32 v2, v92, v0
	v_cvt_pk_bf16_f32 v6, v14, v15
	global_store_dwordx4 v[8:9], v[4:7], off
	s_and_saveexec_b64 s[0:1], vcc
	s_cbranch_execz .LBB0_66
	s_waitcnt lgkmcnt(0)
	v_add_f32_e32 v0, v0, v2
	v_lshl_add_u64 v[2:3], v[80:81], 2, s[50:51]
	global_atomic_add_f32 v[2:3], v0, off
	s_branch .LBB0_66

; template <bool GATE>
; __device__ __forceinline__ void sample_gemm_res(LAS unsigned char* lds, const bf16* Amat, const bf16* Bt, const bf16* Hin, bf16* Hout, float* rss_out, const bf16* PP, const float* rss_in, int bid, int tid) {
;     ...
;   for (int tile = bid; tile < 256; tile += (int)gridDim.x) {
;     const int m0 = TP + (tile & 7) * 64, n0 = (tile >> 3) * 64;
;     const bf16x8* ap = (const bf16x8*)(Amat + (size_t)(m0 + lr) * 2048 + wave * 256 + 8 * kg);
;     const bf16x8* bp = (const bf16x8*)(Bt + (size_t)(n0 + lr) * 2048 + wave * 256 + 8 * kg);
;     const int erow = m0 + (tid >> 3); const size_t ep = (size_t)erow * 2048 + n0 + (tid & 7) * 8;
;     const u32x4 hw = *(const u32x4*)(Hin + ep); u32x4 pw = (u32x4){0u, 0u, 0u, 0u}; float rsi = 0.f; if (GATE) { pw = *(const u32x4*)(PP + ep); rsi = rss_in[erow]; }
;     f32x4m acc[4][4];
; #pragma unroll
;     for (int mi = 0; mi < 4; ++mi)
; #pragma unroll
;         for (int ni = 0; ni < 4; ++ni) acc[mi][ni] = (f32x4m){0.f, 0.f, 0.f, 0.f};
; #pragma unroll 2
;     for (int ks = 0; ks < 8; ++ks) { bf16x8 a[4], b[4];
; #pragma unroll
;         for (int q = 0; q < 4; ++q) { a[q] = ap[(size_t)q * 16 * 256 + ks * 4]; b[q] = bp[(size_t)q * 16 * 256 + ks * 4]; }
; #pragma unroll
;         for (int mi = 0; mi < 4; ++mi)
; #pragma unroll
;             for (int ni = 0; ni < 4; ++ni) acc[mi][ni] = __builtin_amdgcn_mfma_f32_16x16x32_bf16(a[mi], b[ni], acc[mi][ni], 0, 0, 0); }
.LBB0_115:
	s_lshl_b32 s0, s6, 6
	s_and_b32 s1, s0, 0x1c0
	v_add_u32_e32 v0, s1, v84
	s_lshl_b32 s0, s6, 3
	v_add_u32_e32 v76, 0x2000, v0
	s_andn2_b32 s0, s0, 63
	v_ashrrev_i32_e32 v77, 31, v76
	v_lshlrev_b64 v[2:3], 11, v[76:77]
	s_ashr_i32 s1, s0, 31
	v_lshl_add_u64 v[78:79], v[2:3], 0, s[0:1]
	v_or_b32_e32 v78, v78, v70
	v_lshl_add_u64 v[2:3], v[78:79], 1, s[46:47]
	global_load_dwordx4 v[2:5], v[2:3], off
	s_and_b32 s0, s3, 0xffffffc0
	v_or_b32_e32 v6, s0, v71
	v_ashrrev_i32_e32 v7, 31, v6
	v_lshlrev_b64 v[6:7], 12, v[6:7]
	s_and_b32 s0, s2, 0x1c0
	v_lshl_add_u64 v[80:81], v[72:73], 0, v[6:7]
	v_add_lshl_u32 v0, v91, s0, 12
	v_mov_b32_e32 v6, 0
	v_lshl_add_u64 v[82:83], v[74:75], 0, v[0:1]
	s_mov_b64 s[4:5], 0
	v_mov_b32_e32 v7, v6
	v_mov_b32_e32 v8, v6
	v_mov_b32_e32 v9, v6
	v_mov_b32_e32 v10, v6
	v_mov_b32_e32 v11, v6
	v_mov_b32_e32 v12, v6
	v_mov_b32_e32 v13, v6
	v_mov_b32_e32 v14, v6
	v_mov_b32_e32 v15, v6
	v_mov_b32_e32 v16, v6
	v_mov_b32_e32 v17, v6
	v_mov_b32_e32 v18, v6
	v_mov_b32_e32 v19, v6
	v_mov_b32_e32 v20, v6
	v_mov_b32_e32 v21, v6
	v_mov_b32_e32 v22, v6
	v_mov_b32_e32 v23, v6
	v_mov_b32_e32 v24, v6
	v_mov_b32_e32 v25, v6
	v_mov_b32_e32 v30, v6
	v_mov_b32_e32 v31, v6
	v_mov_b32_e32 v32, v6
	v_mov_b32_e32 v33, v6
	v_mov_b32_e32 v26, v6
	v_mov_b32_e32 v27, v6
	v_mov_b32_e32 v28, v6
	v_mov_b32_e32 v29, v6
	v_mov_b32_e32 v34, v6
	v_mov_b32_e32 v35, v6
	v_mov_b32_e32 v36, v6
	v_mov_b32_e32 v37, v6
	v_mov_b32_e32 v38, v6
	v_mov_b32_e32 v39, v6
	v_mov_b32_e32 v40, v6
	v_mov_b32_e32 v41, v6
	v_mov_b32_e32 v46, v6
	v_mov_b32_e32 v47, v6
	v_mov_b32_e32 v48, v6
	v_mov_b32_e32 v49, v6
	v_mov_b32_e32 v42, v6
	v_mov_b32_e32 v43, v6
	v_mov_b32_e32 v44, v6
	v_mov_b32_e32 v45, v6
	v_mov_b32_e32 v54, v6
	v_mov_b32_e32 v55, v6
	v_mov_b32_e32 v56, v6
	v_mov_b32_e32 v57, v6
	v_mov_b32_e32 v50, v6
	v_mov_b32_e32 v51, v6
	v_mov_b32_e32 v52, v6
	v_mov_b32_e32 v53, v6
	v_mov_b32_e32 v62, v6
	v_mov_b32_e32 v63, v6
	v_mov_b32_e32 v64, v6
	v_mov_b32_e32 v65, v6
	v_mov_b32_e32 v58, v6
	v_mov_b32_e32 v59, v6
	v_mov_b32_e32 v60, v6
	v_mov_b32_e32 v61, v6
	v_mov_b32_e32 v66, v6
	v_mov_b32_e32 v67, v6
	v_mov_b32_e32 v68, v6
	v_mov_b32_e32 v69, v6
	s_mov_b32 s1, 0x10000
	s_mov_b64 s[0:1], 0x10c00000
	v_lshl_add_u64 v[128:129], v[82:83], 0, s[0:1]
	s_mov_b64 s[4:5], 0x0
	v_lshl_add_u64 v[130:131], v[80:81], 0, s[4:5]
	s_mov_b64 s[0:1], 0x10c10000
	v_lshl_add_u64 v[132:133], v[82:83], 0, s[0:1]
	s_mov_b64 s[4:5], 0x10000
	v_lshl_add_u64 v[134:135], v[80:81], 0, s[4:5]
	s_mov_b64 s[0:1], 0x10c20000
	v_lshl_add_u64 v[136:137], v[82:83], 0, s[0:1]
	s_mov_b64 s[4:5], 0x20000
	v_lshl_add_u64 v[138:139], v[80:81], 0, s[4:5]
	s_mov_b64 s[0:1], 0x10c30000
	v_lshl_add_u64 v[140:141], v[82:83], 0, s[0:1]
	s_mov_b64 s[4:5], 0x30000
	v_lshl_add_u64 v[142:143], v[80:81], 0, s[4:5]
	global_load_dwordx4 v[96:99], v[128:129], off
	global_load_dwordx4 v[100:103], v[130:131], off
	global_load_dwordx4 v[104:107], v[132:133], off
	global_load_dwordx4 v[108:111], v[134:135], off
	global_load_dwordx4 v[112:115], v[136:137], off
	global_load_dwordx4 v[116:119], v[138:139], off
	global_load_dwordx4 v[120:123], v[140:141], off
	global_load_dwordx4 v[124:127], v[142:143], off
	global_load_dwordx4 v[144:147], v[128:129], off offset:64
	global_load_dwordx4 v[148:151], v[130:131], off offset:64
	global_load_dwordx4 v[152:155], v[132:133], off offset:64
	global_load_dwordx4 v[156:159], v[134:135], off offset:64
	global_load_dwordx4 v[160:163], v[136:137], off offset:64
	global_load_dwordx4 v[164:167], v[138:139], off offset:64
	global_load_dwordx4 v[168:171], v[140:141], off offset:64
	global_load_dwordx4 v[172:175], v[142:143], off offset:64
	global_load_dwordx4 v[192:195], v[128:129], off offset:128
	global_load_dwordx4 v[196:199], v[130:131], off offset:128
	global_load_dwordx4 v[200:203], v[132:133], off offset:128
	global_load_dwordx4 v[204:207], v[134:135], off offset:128
	global_load_dwordx4 v[208:211], v[136:137], off offset:128
	global_load_dwordx4 v[236:239], v[138:139], off offset:128
	global_load_dwordx4 v[240:243], v[140:141], off offset:128
	global_load_dwordx4 v[244:247], v[142:143], off offset:128
	s_waitcnt vmcnt(22)
	v_mfma_f32_16x16x32_bf16 v[6:9], v[96:99], v[100:103], v[6:9]
	s_waitcnt vmcnt(20)
	v_mfma_f32_16x16x32_bf16 v[10:13], v[96:99], v[108:111], v[10:13]
	s_waitcnt vmcnt(18)
	v_mfma_f32_16x16x32_bf16 v[14:17], v[96:99], v[116:119], v[14:17]
	s_waitcnt vmcnt(16)
	v_mfma_f32_16x16x32_bf16 v[18:21], v[96:99], v[124:127], v[18:21]
	v_mfma_f32_16x16x32_bf16 v[22:25], v[104:107], v[100:103], v[22:25]
	v_mfma_f32_16x16x32_bf16 v[30:33], v[104:107], v[108:111], v[30:33]
	v_mfma_f32_16x16x32_bf16 v[26:29], v[104:107], v[116:119], v[26:29]
	v_mfma_f32_16x16x32_bf16 v[34:37], v[104:107], v[124:127], v[34:37]
	v_mfma_f32_16x16x32_bf16 v[38:41], v[112:115], v[100:103], v[38:41]
	v_mfma_f32_16x16x32_bf16 v[46:49], v[112:115], v[108:111], v[46:49]
	v_mfma_f32_16x16x32_bf16 v[42:45], v[112:115], v[116:119], v[42:45]
	v_mfma_f32_16x16x32_bf16 v[54:57], v[112:115], v[124:127], v[54:57]
	v_mfma_f32_16x16x32_bf16 v[50:53], v[120:123], v[100:103], v[50:53]
	v_mfma_f32_16x16x32_bf16 v[62:65], v[120:123], v[108:111], v[62:65]
	v_mfma_f32_16x16x32_bf16 v[58:61], v[120:123], v[116:119], v[58:61]
	v_mfma_f32_16x16x32_bf16 v[66:69], v[120:123], v[124:127], v[66:69]
	global_load_dwordx4 v[96:99], v[128:129], off offset:192
	global_load_dwordx4 v[100:103], v[130:131], off offset:192
	global_load_dwordx4 v[104:107], v[132:133], off offset:192
	global_load_dwordx4 v[108:111], v[134:135], off offset:192
	global_load_dwordx4 v[112:115], v[136:137], off offset:192
	global_load_dwordx4 v[116:119], v[138:139], off offset:192
	global_load_dwordx4 v[120:123], v[140:141], off offset:192
	global_load_dwordx4 v[124:127], v[142:143], off offset:192
	s_waitcnt vmcnt(22)
; template <bool GATE>
; __device__ __forceinline__ void sample_gemm_res(LAS unsigned char* lds, const bf16* Amat, const bf16* Bt, const bf16* Hin, bf16* Hout, float* rss_out, const bf16* PP, const float* rss_in, int bid, int tid) {
;     ...
;     for (int ks = 0; ks < 8; ++ks) { bf16x8 a[4], b[4];
; #pragma unroll
;         for (int q = 0; q < 4; ++q) { a[q] = ap[(size_t)q * 16 * 256 + ks * 4]; b[q] = bp[(size_t)q * 16 * 256 + ks * 4]; }
; #pragma unroll
;         for (int mi = 0; mi < 4; ++mi)
; #pragma unroll
;             for (int ni = 0; ni < 4; ++ni) acc[mi][ni] = __builtin_amdgcn_mfma_f32_16x16x32_bf16(a[mi], b[ni], acc[mi][ni], 0, 0, 0); }
	v_mfma_f32_16x16x32_bf16 v[6:9], v[144:147], v[148:151], v[6:9]
	s_waitcnt vmcnt(20)
	v_mfma_f32_16x16x32_bf16 v[10:13], v[144:147], v[156:159], v[10:13]
	s_waitcnt vmcnt(18)
	v_mfma_f32_16x16x32_bf16 v[14:17], v[144:147], v[164:167], v[14:17]
	s_waitcnt vmcnt(16)
	v_mfma_f32_16x16x32_bf16 v[18:21], v[144:147], v[172:175], v[18:21]
	v_mfma_f32_16x16x32_bf16 v[22:25], v[152:155], v[148:151], v[22:25]
	v_mfma_f32_16x16x32_bf16 v[30:33], v[152:155], v[156:159], v[30:33]
	v_mfma_f32_16x16x32_bf16 v[26:29], v[152:155], v[164:167], v[26:29]
	v_mfma_f32_16x16x32_bf16 v[34:37], v[152:155], v[172:175], v[34:37]
	v_mfma_f32_16x16x32_bf16 v[38:41], v[160:163], v[148:151], v[38:41]
	v_mfma_f32_16x16x32_bf16 v[46:49], v[160:163], v[156:159], v[46:49]
	v_mfma_f32_16x16x32_bf16 v[42:45], v[160:163], v[164:167], v[42:45]
	v_mfma_f32_16x16x32_bf16 v[54:57], v[160:163], v[172:175], v[54:57]
	v_mfma_f32_16x16x32_bf16 v[50:53], v[168:171], v[148:151], v[50:53]
	v_mfma_f32_16x16x32_bf16 v[62:65], v[168:171], v[156:159], v[62:65]
	v_mfma_f32_16x16x32_bf16 v[58:61], v[168:171], v[164:167], v[58:61]
	v_mfma_f32_16x16x32_bf16 v[66:69], v[168:171], v[172:175], v[66:69]
	global_load_dwordx4 v[144:147], v[128:129], off offset:256
	global_load_dwordx4 v[148:151], v[130:131], off offset:256
	global_load_dwordx4 v[152:155], v[132:133], off offset:256
	global_load_dwordx4 v[156:159], v[134:135], off offset:256
	global_load_dwordx4 v[160:163], v[136:137], off offset:256
	global_load_dwordx4 v[164:167], v[138:139], off offset:256
	global_load_dwordx4 v[168:171], v[140:141], off offset:256
	global_load_dwordx4 v[172:175], v[142:143], off offset:256
	s_waitcnt vmcnt(22)
	v_mfma_f32_16x16x32_bf16 v[6:9], v[192:195], v[196:199], v[6:9]
	s_waitcnt vmcnt(20)
	v_mfma_f32_16x16x32_bf16 v[10:13], v[192:195], v[204:207], v[10:13]
	s_waitcnt vmcnt(18)
	v_mfma_f32_16x16x32_bf16 v[14:17], v[192:195], v[236:239], v[14:17]
	s_waitcnt vmcnt(16)
	v_mfma_f32_16x16x32_bf16 v[18:21], v[192:195], v[244:247], v[18:21]
	v_mfma_f32_16x16x32_bf16 v[22:25], v[200:203], v[196:199], v[22:25]
	v_mfma_f32_16x16x32_bf16 v[30:33], v[200:203], v[204:207], v[30:33]
	v_mfma_f32_16x16x32_bf16 v[26:29], v[200:203], v[236:239], v[26:29]
	v_mfma_f32_16x16x32_bf16 v[34:37], v[200:203], v[244:247], v[34:37]
	v_mfma_f32_16x16x32_bf16 v[38:41], v[208:211], v[196:199], v[38:41]
	v_mfma_f32_16x16x32_bf16 v[46:49], v[208:211], v[204:207], v[46:49]
	v_mfma_f32_16x16x32_bf16 v[42:45], v[208:211], v[236:239], v[42:45]
	v_mfma_f32_16x16x32_bf16 v[54:57], v[208:211], v[244:247], v[54:57]
	v_mfma_f32_16x16x32_bf16 v[50:53], v[240:243], v[196:199], v[50:53]
	v_mfma_f32_16x16x32_bf16 v[62:65], v[240:243], v[204:207], v[62:65]
	v_mfma_f32_16x16x32_bf16 v[58:61], v[240:243], v[236:239], v[58:61]
	v_mfma_f32_16x16x32_bf16 v[66:69], v[240:243], v[244:247], v[66:69]
	global_load_dwordx4 v[192:195], v[128:129], off offset:320
	global_load_dwordx4 v[196:199], v[130:131], off offset:320
	global_load_dwordx4 v[200:203], v[132:133], off offset:320
	global_load_dwordx4 v[204:207], v[134:135], off offset:320
	global_load_dwordx4 v[208:211], v[136:137], off offset:320
	global_load_dwordx4 v[236:239], v[138:139], off offset:320
	global_load_dwordx4 v[240:243], v[140:141], off offset:320
	global_load_dwordx4 v[244:247], v[142:143], off offset:320
	s_waitcnt vmcnt(22)
	v_mfma_f32_16x16x32_bf16 v[6:9], v[96:99], v[100:103], v[6:9]
	s_waitcnt vmcnt(20)
	v_mfma_f32_16x16x32_bf16 v[10:13], v[96:99], v[108:111], v[10:13]
	s_waitcnt vmcnt(18)
	v_mfma_f32_16x16x32_bf16 v[14:17], v[96:99], v[116:119], v[14:17]
	s_waitcnt vmcnt(16)
	v_mfma_f32_16x16x32_bf16 v[18:21], v[96:99], v[124:127], v[18:21]
	v_mfma_f32_16x16x32_bf16 v[22:25], v[104:107], v[100:103], v[22:25]
	v_mfma_f32_16x16x32_bf16 v[30:33], v[104:107], v[108:111], v[30:33]
	v_mfma_f32_16x16x32_bf16 v[26:29], v[104:107], v[116:119], v[26:29]
	v_mfma_f32_16x16x32_bf16 v[34:37], v[104:107], v[124:127], v[34:37]
	v_mfma_f32_16x16x32_bf16 v[38:41], v[112:115], v[100:103], v[38:41]
	v_mfma_f32_16x16x32_bf16 v[46:49], v[112:115], v[108:111], v[46:49]
	v_mfma_f32_16x16x32_bf16 v[42:45], v[112:115], v[116:119], v[42:45]
	v_mfma_f32_16x16x32_bf16 v[54:57], v[112:115], v[124:127], v[54:57]
	v_mfma_f32_16x16x32_bf16 v[50:53], v[120:123], v[100:103], v[50:53]
	v_mfma_f32_16x16x32_bf16 v[62:65], v[120:123], v[108:111], v[62:65]
	v_mfma_f32_16x16x32_bf16 v[58:61], v[120:123], v[116:119], v[58:61]
	v_mfma_f32_16x16x32_bf16 v[66:69], v[120:123], v[124:127], v[66:69]
	global_load_dwordx4 v[96:99], v[128:129], off offset:384
	global_load_dwordx4 v[100:103], v[130:131], off offset:384
	global_load_dwordx4 v[104:107], v[132:133], off offset:384
	global_load_dwordx4 v[108:111], v[134:135], off offset:384
	global_load_dwordx4 v[112:115], v[136:137], off offset:384
	global_load_dwordx4 v[116:119], v[138:139], off offset:384
	global_load_dwordx4 v[120:123], v[140:141], off offset:384
	global_load_dwordx4 v[124:127], v[142:143], off offset:384
	s_waitcnt vmcnt(22)
	v_mfma_f32_16x16x32_bf16 v[6:9], v[144:147], v[148:151], v[6:9]
	s_waitcnt vmcnt(20)
	v_mfma_f32_16x16x32_bf16 v[10:13], v[144:147], v[156:159], v[10:13]
	s_waitcnt vmcnt(18)
	v_mfma_f32_16x16x32_bf16 v[14:17], v[144:147], v[164:167], v[14:17]
	s_waitcnt vmcnt(16)
; #define LAS __attribute__((address_space(3)))
; template <bool GATE>
; __device__ __forceinline__ void sample_gemm_res(LAS unsigned char* lds, const bf16* Amat, const bf16* Bt, const bf16* Hin, bf16* Hout, float* rss_out, const bf16* PP, const float* rss_in, int bid, int tid) {
;     ...
;     for (int ks = 0; ks < 8; ++ks) { bf16x8 a[4], b[4];
; #pragma unroll
;         for (int q = 0; q < 4; ++q) { a[q] = ap[(size_t)q * 16 * 256 + ks * 4]; b[q] = bp[(size_t)q * 16 * 256 + ks * 4]; }
; #pragma unroll
;         for (int mi = 0; mi < 4; ++mi)
; #pragma unroll
;             for (int ni = 0; ni < 4; ++ni) acc[mi][ni] = __builtin_amdgcn_mfma_f32_16x16x32_bf16(a[mi], b[ni], acc[mi][ni], 0, 0, 0); }
;     LAS float* red = (LAS float*)lds;
;     __syncthreads();
	v_mfma_f32_16x16x32_bf16 v[18:21], v[144:147], v[172:175], v[18:21]
	v_mfma_f32_16x16x32_bf16 v[22:25], v[152:155], v[148:151], v[22:25]
	v_mfma_f32_16x16x32_bf16 v[30:33], v[152:155], v[156:159], v[30:33]
	v_mfma_f32_16x16x32_bf16 v[26:29], v[152:155], v[164:167], v[26:29]
	v_mfma_f32_16x16x32_bf16 v[34:37], v[152:155], v[172:175], v[34:37]
	v_mfma_f32_16x16x32_bf16 v[38:41], v[160:163], v[148:151], v[38:41]
	v_mfma_f32_16x16x32_bf16 v[46:49], v[160:163], v[156:159], v[46:49]
	v_mfma_f32_16x16x32_bf16 v[42:45], v[160:163], v[164:167], v[42:45]
	v_mfma_f32_16x16x32_bf16 v[54:57], v[160:163], v[172:175], v[54:57]
	v_mfma_f32_16x16x32_bf16 v[50:53], v[168:171], v[148:151], v[50:53]
	v_mfma_f32_16x16x32_bf16 v[62:65], v[168:171], v[156:159], v[62:65]
	v_mfma_f32_16x16x32_bf16 v[58:61], v[168:171], v[164:167], v[58:61]
	v_mfma_f32_16x16x32_bf16 v[66:69], v[168:171], v[172:175], v[66:69]
	global_load_dwordx4 v[144:147], v[128:129], off offset:448
	global_load_dwordx4 v[148:151], v[130:131], off offset:448
	global_load_dwordx4 v[152:155], v[132:133], off offset:448
	global_load_dwordx4 v[156:159], v[134:135], off offset:448
	global_load_dwordx4 v[160:163], v[136:137], off offset:448
	global_load_dwordx4 v[164:167], v[138:139], off offset:448
	global_load_dwordx4 v[168:171], v[140:141], off offset:448
	global_load_dwordx4 v[172:175], v[142:143], off offset:448
	s_waitcnt vmcnt(22)
	v_mfma_f32_16x16x32_bf16 v[6:9], v[192:195], v[196:199], v[6:9]
	s_waitcnt vmcnt(20)
	v_mfma_f32_16x16x32_bf16 v[10:13], v[192:195], v[204:207], v[10:13]
	s_waitcnt vmcnt(18)
	v_mfma_f32_16x16x32_bf16 v[14:17], v[192:195], v[236:239], v[14:17]
	s_waitcnt vmcnt(16)
	v_mfma_f32_16x16x32_bf16 v[18:21], v[192:195], v[244:247], v[18:21]
	v_mfma_f32_16x16x32_bf16 v[22:25], v[200:203], v[196:199], v[22:25]
	v_mfma_f32_16x16x32_bf16 v[30:33], v[200:203], v[204:207], v[30:33]
	v_mfma_f32_16x16x32_bf16 v[26:29], v[200:203], v[236:239], v[26:29]
	v_mfma_f32_16x16x32_bf16 v[34:37], v[200:203], v[244:247], v[34:37]
	v_mfma_f32_16x16x32_bf16 v[38:41], v[208:211], v[196:199], v[38:41]
	v_mfma_f32_16x16x32_bf16 v[46:49], v[208:211], v[204:207], v[46:49]
	v_mfma_f32_16x16x32_bf16 v[42:45], v[208:211], v[236:239], v[42:45]
	v_mfma_f32_16x16x32_bf16 v[54:57], v[208:211], v[244:247], v[54:57]
	v_mfma_f32_16x16x32_bf16 v[50:53], v[240:243], v[196:199], v[50:53]
	v_mfma_f32_16x16x32_bf16 v[62:65], v[240:243], v[204:207], v[62:65]
	v_mfma_f32_16x16x32_bf16 v[58:61], v[240:243], v[236:239], v[58:61]
	v_mfma_f32_16x16x32_bf16 v[66:69], v[240:243], v[244:247], v[66:69]
	s_waitcnt vmcnt(14)
	v_mfma_f32_16x16x32_bf16 v[6:9], v[96:99], v[100:103], v[6:9]
	s_waitcnt vmcnt(12)
	v_mfma_f32_16x16x32_bf16 v[10:13], v[96:99], v[108:111], v[10:13]
	s_waitcnt vmcnt(10)
	v_mfma_f32_16x16x32_bf16 v[14:17], v[96:99], v[116:119], v[14:17]
	s_waitcnt vmcnt(8)
	v_mfma_f32_16x16x32_bf16 v[18:21], v[96:99], v[124:127], v[18:21]
	v_mfma_f32_16x16x32_bf16 v[22:25], v[104:107], v[100:103], v[22:25]
	v_mfma_f32_16x16x32_bf16 v[30:33], v[104:107], v[108:111], v[30:33]
	v_mfma_f32_16x16x32_bf16 v[26:29], v[104:107], v[116:119], v[26:29]
	v_mfma_f32_16x16x32_bf16 v[34:37], v[104:107], v[124:127], v[34:37]
	v_mfma_f32_16x16x32_bf16 v[38:41], v[112:115], v[100:103], v[38:41]
	v_mfma_f32_16x16x32_bf16 v[46:49], v[112:115], v[108:111], v[46:49]
	v_mfma_f32_16x16x32_bf16 v[42:45], v[112:115], v[116:119], v[42:45]
	v_mfma_f32_16x16x32_bf16 v[54:57], v[112:115], v[124:127], v[54:57]
	v_mfma_f32_16x16x32_bf16 v[50:53], v[120:123], v[100:103], v[50:53]
	v_mfma_f32_16x16x32_bf16 v[62:65], v[120:123], v[108:111], v[62:65]
	v_mfma_f32_16x16x32_bf16 v[58:61], v[120:123], v[116:119], v[58:61]
	v_mfma_f32_16x16x32_bf16 v[66:69], v[120:123], v[124:127], v[66:69]
	s_waitcnt vmcnt(6)
	v_mfma_f32_16x16x32_bf16 v[6:9], v[144:147], v[148:151], v[6:9]
	s_waitcnt vmcnt(4)
	v_mfma_f32_16x16x32_bf16 v[10:13], v[144:147], v[156:159], v[10:13]
	s_waitcnt vmcnt(2)
	v_mfma_f32_16x16x32_bf16 v[14:17], v[144:147], v[164:167], v[14:17]
	s_waitcnt vmcnt(0)
	v_mfma_f32_16x16x32_bf16 v[18:21], v[144:147], v[172:175], v[18:21]
	v_mfma_f32_16x16x32_bf16 v[22:25], v[152:155], v[148:151], v[22:25]
	v_mfma_f32_16x16x32_bf16 v[30:33], v[152:155], v[156:159], v[30:33]
	v_mfma_f32_16x16x32_bf16 v[26:29], v[152:155], v[164:167], v[26:29]
	v_mfma_f32_16x16x32_bf16 v[34:37], v[152:155], v[172:175], v[34:37]
	v_mfma_f32_16x16x32_bf16 v[38:41], v[160:163], v[148:151], v[38:41]
	v_mfma_f32_16x16x32_bf16 v[46:49], v[160:163], v[156:159], v[46:49]
	v_mfma_f32_16x16x32_bf16 v[42:45], v[160:163], v[164:167], v[42:45]
	v_mfma_f32_16x16x32_bf16 v[54:57], v[160:163], v[172:175], v[54:57]
	v_mfma_f32_16x16x32_bf16 v[50:53], v[168:171], v[148:151], v[50:53]
	v_mfma_f32_16x16x32_bf16 v[62:65], v[168:171], v[156:159], v[62:65]
	v_mfma_f32_16x16x32_bf16 v[58:61], v[168:171], v[164:167], v[58:61]
	v_mfma_f32_16x16x32_bf16 v[66:69], v[168:171], v[172:175], v[66:69]
	v_add_u32_e32 v0, 0x1000, v89
	s_barrier
; __device__ __forceinline__ unsigned cvtpk(float lo, float hi) { f32x2_t v = {lo, hi}; bf16x2_t b = __builtin_convertvector(v, bf16x2_t); return __builtin_bit_cast(unsigned, b); }
; template <bool GATE>
; __device__ __forceinline__ void sample_gemm_res(LAS unsigned char* lds, const bf16* Amat, const bf16* Bt, const bf16* Hin, bf16* Hout, float* rss_out, const bf16* PP, const float* rss_in, int bid, int tid) {
;     ...
; #pragma unroll
;     for (int mi = 0; mi < 4; ++mi)
; #pragma unroll
;         for (int ni = 0; ni < 4; ++ni)
; #pragma unroll
;             for (int i = 0; i < 4; ++i) red[(wave * 64 + 16 * mi + kg * 4 + i) * 65 + 16 * ni + lr] = acc[mi][ni][i];
;     __syncthreads();
;     { const int row = tid >> 3, c8 = (tid & 7) * 8, grow = m0 + row; float v[8];
; #pragma unroll
;       for (int e = 0; e < 8; ++e) { float sacc = 0.f;
; #pragma unroll
;           for (int w = 0; w < 8; ++w) sacc += red[(w * 64 + row) * 65 + c8 + e];
;           v[e] = sacc; }
;       float sc = 1.f; if (GATE) sc = rsqrtf(rsi * (1.f / 2048.f) + 1e-6f);
;       const size_t p = (size_t)grow * 2048 + n0 + c8;
;       const unsigned hws[4] = {hw.x, hw.y, hw.z, hw.w}, pws[4] = {pw.x, pw.y, pw.z, pw.w}; unsigned ow[4]; float sq = 0.f;
; #pragma unroll
;       for (int e2 = 0; e2 < 4; ++e2) { float h0 = __uint_as_float(hws[e2] << 16), h1 = __uint_as_float(hws[e2] & 0xffff0000u);
;           if (GATE) { h0 += __builtin_amdgcn_rcpf(1.f + __expf(-sc * v[2 * e2])) * __uint_as_float(pws[e2] << 16); h1 += __builtin_amdgcn_rcpf(1.f + __expf(-sc * v[2 * e2 + 1])) * __uint_as_float(pws[e2] & 0xffff0000u); }
;           else { h0 += v[2 * e2]; h1 += v[2 * e2 + 1]; }
;           sq += h0 * h0 + h1 * h1; ow[e2] = cvtpk(h0, h1); }
;       *(u32x4*)(Hout + p) = (u32x4){ow[0], ow[1], ow[2], ow[3]};
;       sq += __shfl_xor(sq, 1); sq += __shfl_xor(sq, 2); sq += __shfl_xor(sq, 4);
;       if ((tid & 7) == 0) atomicAdd(rss_out + grow, sq); }
;     __syncthreads();
	ds_write2_b32 v89, v6, v10 offset1:16
	ds_write2_b32 v89, v7, v11 offset0:65 offset1:81
	ds_write2_b32 v89, v8, v12 offset0:130 offset1:146
	ds_write2_b32 v89, v9, v13 offset0:195 offset1:211
	ds_write2_b32 v89, v14, v18 offset0:32 offset1:48
	ds_write2_b32 v89, v15, v19 offset0:97 offset1:113
	ds_write2_b32 v89, v16, v20 offset0:162 offset1:178
	ds_write2_b32 v89, v17, v21 offset0:227 offset1:243
	ds_write2_b32 v0, v22, v30 offset0:16 offset1:32
	ds_write2_b32 v0, v23, v31 offset0:81 offset1:97
	ds_write2_b32 v0, v24, v32 offset0:146 offset1:162
	ds_write2_b32 v0, v25, v33 offset0:211 offset1:227
	ds_write2_b32 v0, v26, v34 offset0:48 offset1:64
	ds_write2_b32 v0, v27, v35 offset0:113 offset1:129
	ds_write2_b32 v0, v28, v36 offset0:178 offset1:194
	v_add_u32_e32 v0, 0x1200, v89
	ds_write2_b32 v0, v29, v37 offset0:115 offset1:131
	v_add_u32_e32 v0, 0x2000, v89
	ds_write2_b32 v0, v38, v46 offset0:32 offset1:48
	ds_write2_b32 v0, v39, v47 offset0:97 offset1:113
	ds_write2_b32 v0, v40, v48 offset0:162 offset1:178
	ds_write2_b32 v0, v41, v49 offset0:227 offset1:243
	ds_write2_b32 v0, v42, v54 offset0:64 offset1:80
	ds_write2_b32 v0, v43, v55 offset0:129 offset1:145
	ds_write2_b32 v0, v44, v56 offset0:194 offset1:210
	v_add_u32_e32 v0, 0x2400, v89
	ds_write2_b32 v0, v45, v57 offset0:3 offset1:19
	v_add_u32_e32 v0, 0x3000, v89
	v_add_u32_e32 v6, 0x3200, v89
	ds_write2_b32 v0, v50, v62 offset0:48 offset1:64
	ds_write2_b32 v0, v51, v63 offset0:113 offset1:129
	ds_write2_b32 v0, v52, v64 offset0:178 offset1:194
	ds_write2_b32 v6, v53, v65 offset0:115 offset1:131
	ds_write2_b32 v0, v58, v66 offset0:80 offset1:96
	ds_write2_b32 v0, v59, v67 offset0:145 offset1:161
	ds_write2_b32 v0, v60, v68 offset0:210 offset1:226
	v_add_u32_e32 v0, 0x3400, v89
	ds_write2_b32 v0, v61, v69 offset0:19 offset1:35
	v_add_u32_e32 v0, v85, v90
	s_waitcnt lgkmcnt(0)
	s_barrier
	ds_read2_b32 v[6:7], v0 offset1:1
	v_add_u32_e32 v8, 0x4100, v0
	v_add_u32_e32 v10, 0x8200, v0
	v_add_u32_e32 v12, 0xc300, v0
	ds_read2_b32 v[8:9], v8 offset1:1
	ds_read2_b32 v[10:11], v10 offset1:1
	ds_read2_b32 v[12:13], v12 offset1:1
	ds_read2_b32 v[14:15], v0 offset0:2 offset1:3
	ds_read2_b32 v[16:17], v0 offset0:4 offset1:5
	ds_read2_b32 v[18:19], v0 offset0:6 offset1:7
	s_waitcnt lgkmcnt(6)
	v_pk_add_f32 v[6:7], v[6:7], 0 op_sel_hi:[1,0]
	ds_read2_b32 v[20:21], v92 offset1:1
	s_waitcnt lgkmcnt(6)
	v_pk_add_f32 v[6:7], v[6:7], v[8:9]
	ds_read2_b32 v[8:9], v93 offset1:1
	s_waitcnt lgkmcnt(6)
	v_pk_add_f32 v[6:7], v[6:7], v[10:11]
	s_waitcnt lgkmcnt(4)
	v_pk_add_f32 v[14:15], v[14:15], 0 op_sel_hi:[1,0]
	v_pk_add_f32 v[6:7], v[6:7], v[12:13]
	v_add_u32_e32 v42, 0xc308, v0
	s_waitcnt lgkmcnt(1)
	v_pk_add_f32 v[6:7], v[6:7], v[20:21]
	ds_read2_b32 v[10:11], v92 offset0:2 offset1:3
	ds_read2_b32 v[12:13], v92 offset0:4 offset1:5
	ds_read2_b32 v[20:21], v92 offset0:6 offset1:7
	s_waitcnt lgkmcnt(3)
	v_pk_add_f32 v[6:7], v[6:7], v[8:9]
	ds_read2_b32 v[8:9], v94 offset1:1
	ds_read2_b32 v[22:23], v95 offset1:1
	ds_read2_b32 v[24:25], v93 offset0:2 offset1:3
	ds_read2_b32 v[26:27], v93 offset0:4 offset1:5
	ds_read2_b32 v[28:29], v93 offset0:6 offset1:7
	s_waitcnt lgkmcnt(4)
	v_pk_add_f32 v[6:7], v[6:7], v[8:9]
	ds_read2_b32 v[8:9], v94 offset0:2 offset1:3
	ds_read2_b32 v[30:31], v94 offset0:4 offset1:5
	ds_read2_b32 v[32:33], v94 offset0:6 offset1:7
	s_waitcnt lgkmcnt(6)
	v_pk_add_f32 v[6:7], v[6:7], v[22:23]
	v_lshlrev_b32_e32 v22, 16, v2
	v_and_b32_e32 v23, 0xffff0000, v2
	v_add_u32_e32 v2, 0x4108, v0
	ds_read2_b32 v[34:35], v2 offset1:1
	v_add_u32_e32 v2, 0x8208, v0
	ds_read2_b32 v[36:37], v95 offset0:2 offset1:3
	ds_read2_b32 v[38:39], v95 offset0:4 offset1:5
	ds_read2_b32 v[40:41], v95 offset0:6 offset1:7
	v_add_u32_e32 v46, 0x8210, v0
	v_pk_add_f32 v[6:7], v[6:7], v[22:23]
	s_waitcnt lgkmcnt(3)
	v_pk_add_f32 v[14:15], v[14:15], v[34:35]
	ds_read2_b32 v[34:35], v2 offset1:1
	ds_read2_b32 v[42:43], v42 offset1:1
	v_add_u32_e32 v2, 0x4110, v0
	ds_read2_b32 v[44:45], v2 offset1:1
	ds_read2_b32 v[46:47], v46 offset1:1
	v_lshlrev_b32_e32 v2, 16, v3
	s_waitcnt lgkmcnt(3)
	v_pk_add_f32 v[14:15], v[14:15], v[34:35]
	v_and_b32_e32 v3, 0xffff0000, v3
	s_waitcnt lgkmcnt(2)
	v_pk_add_f32 v[14:15], v[14:15], v[42:43]
	v_pk_mul_f32 v[22:23], v[6:7], v[6:7]
	v_pk_add_f32 v[10:11], v[14:15], v[10:11]
	v_add_u32_e32 v14, 0xc310, v0
	ds_read2_b32 v[14:15], v14 offset1:1
	v_pk_add_f32 v[10:11], v[10:11], v[24:25]
	v_add_u32_e32 v24, 0x8218, v0
	v_pk_add_f32 v[8:9], v[10:11], v[8:9]
	v_pk_add_f32 v[10:11], v[16:17], 0 op_sel_hi:[1,0]
	v_add_u32_e32 v16, 0x4118, v0
	s_waitcnt lgkmcnt(2)
	v_pk_add_f32 v[10:11], v[10:11], v[44:45]
	v_add_u32_e32 v0, 0xc318, v0
	ds_read2_b32 v[16:17], v16 offset1:1
	ds_read2_b32 v[24:25], v24 offset1:1
	ds_read2_b32 v[34:35], v0 offset1:1
	s_waitcnt lgkmcnt(4)
	v_pk_add_f32 v[10:11], v[10:11], v[46:47]
	v_pk_add_f32 v[8:9], v[8:9], v[36:37]
	s_waitcnt lgkmcnt(3)
	v_pk_add_f32 v[10:11], v[10:11], v[14:15]
	v_pk_add_f32 v[14:15], v[18:19], 0 op_sel_hi:[1,0]
	v_pk_add_f32 v[10:11], v[10:11], v[12:13]
	s_waitcnt lgkmcnt(2)
	v_pk_add_f32 v[14:15], v[14:15], v[16:17]
	v_pk_add_f32 v[10:11], v[10:11], v[26:27]
	s_waitcnt lgkmcnt(1)
	v_pk_add_f32 v[14:15], v[14:15], v[24:25]
	v_pk_add_f32 v[10:11], v[10:11], v[30:31]
	s_waitcnt lgkmcnt(0)
	v_pk_add_f32 v[14:15], v[14:15], v[34:35]
	v_pk_add_f32 v[2:3], v[8:9], v[2:3]
	v_pk_add_f32 v[14:15], v[14:15], v[20:21]
	v_pk_add_f32 v[10:11], v[10:11], v[38:39]
	v_pk_add_f32 v[14:15], v[14:15], v[28:29]
	v_lshlrev_b32_e32 v12, 16, v4
	v_and_b32_e32 v13, 0xffff0000, v4
	v_pk_add_f32 v[14:15], v[14:15], v[32:33]
	v_pk_mul_f32 v[8:9], v[2:3], v[2:3]
	v_pk_add_f32 v[10:11], v[10:11], v[12:13]
	v_pk_add_f32 v[14:15], v[14:15], v[40:41]
	v_lshlrev_b32_e32 v4, 16, v5
	v_and_b32_e32 v5, 0xffff0000, v5
	v_pk_mul_f32 v[12:13], v[10:11], v[10:11]
	v_pk_add_f32 v[14:15], v[14:15], v[4:5]
	v_add_f32_e32 v0, v8, v9
	v_add_f32_e32 v8, v22, v23
	v_pk_mul_f32 v[4:5], v[14:15], v[14:15]
	v_add_f32_e32 v0, v8, v0
	v_add_f32_e32 v8, v12, v13
	v_add_f32_e32 v0, v0, v8
	v_add_f32_e32 v4, v4, v5
	v_add_f32_e32 v0, v0, v4
	ds_bpermute_b32 v4, v86, v0
	v_cvt_pk_bf16_f32 v5, v2, v3
	s_waitcnt lgkmcnt(0)
	v_add_f32_e32 v0, v0, v4
	ds_bpermute_b32 v8, v87, v0
	v_cvt_pk_bf16_f32 v4, v6, v7
	v_cvt_pk_bf16_f32 v6, v10, v11
	v_cvt_pk_bf16_f32 v7, v14, v15
	s_waitcnt lgkmcnt(0)
	v_add_f32_e32 v0, v0, v8
	ds_bpermute_b32 v2, v88, v0
	v_lshl_add_u64 v[8:9], v[78:79], 1, s[48:49]
	global_store_dwordx4 v[8:9], v[4:7], off
	s_and_saveexec_b64 s[0:1], vcc
	s_cbranch_execz .LBB0_114
	s_waitcnt lgkmcnt(0)
	v_add_f32_e32 v0, v0, v2
	v_lshl_add_u64 v[2:3], v[76:77], 2, s[50:51]
	global_atomic_add_f32 v[2:3], v0, off
	s_branch .LBB0_114

; __device__ __forceinline__ void xcd_barrier(const XcdBarrier& b) {
;     asm volatile("s_waitcnt vmcnt(0)" ::: "memory");
;     __syncthreads();
;     if (threadIdx.x == 0) {
;         unsigned* bar = b.bar;
;         __builtin_amdgcn_s_waitcnt(0);
;         unsigned nloc = b.st[0], nx = b.st[1];
;         if (nloc == 0u) { xcd_barrier_complete(bar, b.x, nloc, nx); b.st[0] = nloc; b.st[1] = nx; }
; __global__ void __launch_bounds__(NTHR, 2) mega_fwd(Args A) {
;     ...
;         if (ph + 1 < A.ph_hi) { if (ph == A.ph_lo) cg::this_grid().sync(); else xcd_barrier(xbar); }
.LBB0_1008:
	s_waitcnt vmcnt(0)
	s_waitcnt lgkmcnt(0)
	s_barrier
	s_mov_b64 s[0:1], exec
	v_readlane_b32 s2, v251, 2
	v_readlane_b32 s3, v251, 3
	s_and_b64 s[2:3], s[0:1], s[2:3]
	s_mov_b64 exec, s[2:3]
	s_cbranch_execz .LBB0_1061
	v_readlane_b32 s2, v254, 10
	s_waitcnt vmcnt(0) expcnt(0) lgkmcnt(0)
	s_nop 0
	v_mov_b32_e32 v0, s2
	ds_read_b32 v3, v0
	v_readlane_b32 s2, v254, 11
	s_waitcnt lgkmcnt(0)
	v_cmp_ne_u32_e32 vcc, 0, v3
	v_mov_b32_e32 v0, s2
	ds_read_b32 v2, v0
	s_cbranch_vccnz .LBB0_1025
	v_readlane_b32 s4, v251, 0
	v_readlane_b32 s5, v251, 1
	s_load_dwordx2 s[2:3], s[4:5], 0x4
	s_mov_b32 s9, 1
	s_waitcnt lgkmcnt(0)
	s_mul_i32 s8, s2, s92
	s_mul_i32 s8, s8, s3
	s_branch .LBB0_1013
